# P1 epilogue: stores of each workgroup's LAST unit are write-through (sc0 sc1) so barrier 2's L2 writeback finds little dirty data
# speedup vs baseline: 1.0298x; 1.0014x over previous
.LBB0_168:
	s_lshl_b32 s12, s8, 8
	s_add_i32 s12, s12, s41
	v_or_b32_e32 v114, s12, v1
	s_mov_b64 s[0:1], -1
	s_cmp_gt_i32 s68, 11
	v_add_u32_e32 v174, 0x80, v114
	s_cbranch_scc0 .LBB0_171
	s_cmp_lt_u32 s68, 16
	s_cselect_b64 s[0:1], -1, 0
	s_lshl_b32 s13, s68, 8
	s_and_b64 s[8:9], s[0:1], exec
	s_cselect_b32 s8, s74, 0xfffff000
	s_cselect_b32 s20, 0x2000, s40
	s_add_i32 s13, s8, s13
	s_and_b64 s[8:9], s[0:1], exec
	s_cselect_b32 s8, s55, s49
	s_cselect_b32 s9, s54, s48
	v_mov_b32_e32 v117, s8
	s_sub_u32 s8, 32, s20
	v_mov_b32_e32 v116, s9
	s_subb_u32 s9, 0, 0
	v_mov_b32_e32 v115, s9
	v_cndmask_b32_e64 v119, v115, 0, s[4:5]
	v_mov_b32_e32 v115, s8
	s_and_b64 s[0:1], s[0:1], exec
	v_or_b32_e32 v154, s13, v176
	v_cndmask_b32_e64 v118, v115, 0, s[4:5]
	v_ashrrev_i32_e32 v115, 31, v114
	s_cselect_b32 s0, 10, 11
	v_lshl_add_u64 v[116:117], v[154:155], 1, v[116:117]
	v_lshlrev_b64 v[128:129], s0, v[114:115]
	v_cvt_pk_bf16_f32 v115, v142, v143
	v_cvt_pk_bf16_f32 v121, v144, v145
	v_cvt_pk_bf16_f32 v122, v138, v139
	v_cvt_pk_bf16_f32 v123, v140, v141
	v_cvt_pk_bf16_f32 v124, v134, v135
	v_mov_b32_e32 v154, v155
	v_cndmask_b32_e64 v120, v115, v124, s[4:5]
	v_cvt_pk_bf16_f32 v125, v136, v137
	v_cvt_pk_bf16_f32 v126, v130, v131
	v_cvt_pk_bf16_f32 v127, v132, v133
	v_lshl_add_u64 v[128:129], v[128:129], 1, v[116:117]
	v_lshlrev_b64 v[118:119], 1, v[118:119]
	v_mov_b32_dpp v154, v120 row_ror:8 row_mask:0xf bank_mask:0xf
	v_cndmask_b32_e64 v120, v154, v115, s[4:5]
	v_cndmask_b32_e64 v124, v124, v154, s[4:5]
	v_cndmask_b32_e64 v115, v121, v125, s[4:5]
	v_mov_b32_e32 v154, v155
	v_lshl_add_u64 v[182:183], v[128:129], 0, v[118:119]
	v_mov_b32_e32 v175, v155
	v_mov_b32_dpp v154, v115 row_ror:8 row_mask:0xf bank_mask:0xf
	v_cndmask_b32_e64 v121, v154, v121, s[4:5]
	v_cndmask_b32_e64 v125, v125, v154, s[4:5]
	v_cndmask_b32_e64 v115, v122, v126, s[4:5]
	v_mov_b32_e32 v154, v155
	s_nop 1
	v_mov_b32_dpp v154, v115 row_ror:8 row_mask:0xf bank_mask:0xf
	v_cndmask_b32_e64 v122, v154, v122, s[4:5]
	v_cndmask_b32_e64 v126, v126, v154, s[4:5]
	v_cndmask_b32_e64 v115, v123, v127, s[4:5]
	v_mov_b32_e32 v154, v155
	s_nop 1
	v_mov_b32_dpp v154, v115 row_ror:8 row_mask:0xf bank_mask:0xf
	v_mov_b32_e32 v115, s20
	v_cndmask_b32_e64 v115, 32, v115, s[4:5]
	v_cndmask_b32_e64 v123, v154, v123, s[4:5]
	v_cndmask_b32_e64 v127, v127, v154, s[4:5]
	v_lshlrev_b32_e32 v154, 1, v115
	s_cmp_lg_u64 s[6:7], 0
	s_cbranch_scc0 .Lp1wt_0
	global_store_dwordx4 v[182:183], v[120:123], off
	s_branch .Lp1wt_0_e
.Lp1wt_0:
	global_store_dwordx4 v[182:183], v[120:123], off sc0 sc1
.Lp1wt_0_e:
	s_nop 1
	v_lshl_add_u64 v[120:121], v[128:129], 0, v[154:155]
	s_cmp_lg_u64 s[6:7], 0
	s_cbranch_scc0 .Lp1wt_1
	global_store_dwordx4 v[120:121], v[124:127], off
	s_branch .Lp1wt_1_e
.Lp1wt_1:
	global_store_dwordx4 v[120:121], v[124:127], off sc0 sc1
.Lp1wt_1_e:
	v_or_b32_e32 v120, 16, v114
	v_ashrrev_i32_e32 v121, 31, v120
	v_lshlrev_b64 v[128:129], s0, v[120:121]
	v_cvt_pk_bf16_f32 v115, v110, v111
	v_cvt_pk_bf16_f32 v121, v112, v113
	v_cvt_pk_bf16_f32 v122, v106, v107
	v_cvt_pk_bf16_f32 v123, v108, v109
	v_cvt_pk_bf16_f32 v124, v102, v103
	v_cvt_pk_bf16_f32 v125, v104, v105
	v_cvt_pk_bf16_f32 v126, v98, v99
	v_cvt_pk_bf16_f32 v127, v100, v101
	v_lshl_add_u64 v[128:129], v[128:129], 1, v[116:117]
	v_cndmask_b32_e64 v120, v115, v124, s[4:5]
	v_lshl_add_u64 v[182:183], v[128:129], 0, v[118:119]
	s_nop 0
	v_mov_b32_dpp v175, v120 row_ror:8 row_mask:0xf bank_mask:0xf
	v_cndmask_b32_e64 v120, v175, v115, s[4:5]
	v_cndmask_b32_e64 v124, v124, v175, s[4:5]
	v_cndmask_b32_e64 v115, v121, v125, s[4:5]
	v_mov_b32_e32 v175, v155
	s_nop 1
	v_mov_b32_dpp v175, v115 row_ror:8 row_mask:0xf bank_mask:0xf
	v_cndmask_b32_e64 v121, v175, v121, s[4:5]
	v_cndmask_b32_e64 v125, v125, v175, s[4:5]
	v_cndmask_b32_e64 v115, v122, v126, s[4:5]
	v_mov_b32_e32 v175, v155
	s_nop 1
	v_mov_b32_dpp v175, v115 row_ror:8 row_mask:0xf bank_mask:0xf
	v_cndmask_b32_e64 v122, v175, v122, s[4:5]
	v_cndmask_b32_e64 v126, v126, v175, s[4:5]
	v_cndmask_b32_e64 v115, v123, v127, s[4:5]
	v_mov_b32_e32 v175, v155
	s_nop 1
	v_mov_b32_dpp v175, v115 row_ror:8 row_mask:0xf bank_mask:0xf
	v_cndmask_b32_e64 v123, v175, v123, s[4:5]
	v_cndmask_b32_e64 v127, v127, v175, s[4:5]
	s_cmp_lg_u64 s[6:7], 0
	s_cbranch_scc0 .Lp1wt_2
	global_store_dwordx4 v[182:183], v[120:123], off
	s_branch .Lp1wt_2_e

.Lp1wt_2_e:
	v_mov_b32_e32 v175, v155
	s_nop 0
	v_lshl_add_u64 v[120:121], v[128:129], 0, v[154:155]
	s_cmp_lg_u64 s[6:7], 0
	s_cbranch_scc0 .Lp1wt_3
	global_store_dwordx4 v[120:121], v[124:127], off
	s_branch .Lp1wt_3_e

.Lp1wt_3_e:
	v_or_b32_e32 v120, 32, v114
	v_ashrrev_i32_e32 v121, 31, v120
	v_lshlrev_b64 v[128:129], s0, v[120:121]
	v_cvt_pk_bf16_f32 v115, v94, v95
	v_cvt_pk_bf16_f32 v121, v96, v97
	v_cvt_pk_bf16_f32 v122, v90, v91
	v_cvt_pk_bf16_f32 v123, v92, v93
	v_cvt_pk_bf16_f32 v124, v86, v87
	v_cvt_pk_bf16_f32 v125, v88, v89
	v_cvt_pk_bf16_f32 v126, v82, v83
	v_cvt_pk_bf16_f32 v127, v84, v85
	v_lshl_add_u64 v[128:129], v[128:129], 1, v[116:117]
	v_cndmask_b32_e64 v120, v115, v124, s[4:5]
	v_lshl_add_u64 v[182:183], v[128:129], 0, v[118:119]
	s_nop 0
	v_mov_b32_dpp v175, v120 row_ror:8 row_mask:0xf bank_mask:0xf
	v_cndmask_b32_e64 v120, v175, v115, s[4:5]
	v_cndmask_b32_e64 v124, v124, v175, s[4:5]
	v_cndmask_b32_e64 v115, v121, v125, s[4:5]
	v_mov_b32_e32 v175, v155
	s_nop 1
	v_mov_b32_dpp v175, v115 row_ror:8 row_mask:0xf bank_mask:0xf
	v_cndmask_b32_e64 v121, v175, v121, s[4:5]
	v_cndmask_b32_e64 v125, v125, v175, s[4:5]
	v_cndmask_b32_e64 v115, v122, v126, s[4:5]
	v_mov_b32_e32 v175, v155
	s_nop 1
	v_mov_b32_dpp v175, v115 row_ror:8 row_mask:0xf bank_mask:0xf
	v_cndmask_b32_e64 v122, v175, v122, s[4:5]
	v_cndmask_b32_e64 v126, v126, v175, s[4:5]
	v_cndmask_b32_e64 v115, v123, v127, s[4:5]
	v_mov_b32_e32 v175, v155
	s_nop 1
	v_mov_b32_dpp v175, v115 row_ror:8 row_mask:0xf bank_mask:0xf
	v_cndmask_b32_e64 v123, v175, v123, s[4:5]
	v_cndmask_b32_e64 v127, v127, v175, s[4:5]
	s_cmp_lg_u64 s[6:7], 0
	s_cbranch_scc0 .Lp1wt_4
	global_store_dwordx4 v[182:183], v[120:123], off
	s_branch .Lp1wt_4_e

.Lp1wt_5_e:
	v_or_b32_e32 v120, 48, v114
	v_ashrrev_i32_e32 v121, 31, v120
	v_lshlrev_b64 v[128:129], s0, v[120:121]
	v_cvt_pk_bf16_f32 v115, v78, v79
	v_cvt_pk_bf16_f32 v121, v80, v81
	v_cvt_pk_bf16_f32 v122, v74, v75
	v_cvt_pk_bf16_f32 v123, v76, v77
	v_cvt_pk_bf16_f32 v124, v70, v71
	v_cvt_pk_bf16_f32 v125, v72, v73
	v_cvt_pk_bf16_f32 v126, v66, v67
	v_cvt_pk_bf16_f32 v127, v68, v69
	v_lshl_add_u64 v[128:129], v[128:129], 1, v[116:117]
	v_cndmask_b32_e64 v120, v115, v124, s[4:5]
	v_lshl_add_u64 v[182:183], v[128:129], 0, v[118:119]
	s_nop 0
	v_mov_b32_dpp v175, v120 row_ror:8 row_mask:0xf bank_mask:0xf
	v_cndmask_b32_e64 v120, v175, v115, s[4:5]
	v_cndmask_b32_e64 v124, v124, v175, s[4:5]
	v_cndmask_b32_e64 v115, v121, v125, s[4:5]
	v_mov_b32_e32 v175, v155
	s_nop 1
	v_mov_b32_dpp v175, v115 row_ror:8 row_mask:0xf bank_mask:0xf
	v_cndmask_b32_e64 v121, v175, v121, s[4:5]
	v_cndmask_b32_e64 v125, v125, v175, s[4:5]
	v_cndmask_b32_e64 v115, v122, v126, s[4:5]
	v_mov_b32_e32 v175, v155
	s_nop 1
	v_mov_b32_dpp v175, v115 row_ror:8 row_mask:0xf bank_mask:0xf
	v_cndmask_b32_e64 v122, v175, v122, s[4:5]
	v_cndmask_b32_e64 v126, v126, v175, s[4:5]
	v_cndmask_b32_e64 v115, v123, v127, s[4:5]
	v_mov_b32_e32 v175, v155
	s_nop 1
	v_mov_b32_dpp v175, v115 row_ror:8 row_mask:0xf bank_mask:0xf
	v_cndmask_b32_e64 v123, v175, v123, s[4:5]
	v_cndmask_b32_e64 v127, v127, v175, s[4:5]
	s_cmp_lg_u64 s[6:7], 0
	s_cbranch_scc0 .Lp1wt_6
	global_store_dwordx4 v[182:183], v[120:123], off
	s_branch .Lp1wt_6_e

.Lp1wt_6_e:
	v_ashrrev_i32_e32 v175, 31, v174
	s_nop 0
	v_lshl_add_u64 v[120:121], v[128:129], 0, v[154:155]
	s_cmp_lg_u64 s[6:7], 0
	s_cbranch_scc0 .Lp1wt_7
	global_store_dwordx4 v[120:121], v[124:127], off
	s_branch .Lp1wt_7_e

.Lp1wt_7_e:
	v_lshlrev_b64 v[128:129], s0, v[174:175]
	v_cvt_pk_bf16_f32 v115, v62, v63
	v_cvt_pk_bf16_f32 v121, v64, v65
	v_cvt_pk_bf16_f32 v122, v58, v59
	v_cvt_pk_bf16_f32 v123, v60, v61
	s_nop 0
	v_cvt_pk_bf16_f32 v124, v54, v55
	v_mov_b32_e32 v175, v155
	v_cndmask_b32_e64 v120, v115, v124, s[4:5]
	v_cvt_pk_bf16_f32 v125, v56, v57
	v_cvt_pk_bf16_f32 v126, v50, v51
	v_cvt_pk_bf16_f32 v127, v52, v53
	v_lshl_add_u64 v[128:129], v[128:129], 1, v[116:117]
	v_lshl_add_u64 v[182:183], v[128:129], 0, v[118:119]
	v_mov_b32_dpp v175, v120 row_ror:8 row_mask:0xf bank_mask:0xf
	v_cndmask_b32_e64 v120, v175, v115, s[4:5]
	v_cndmask_b32_e64 v124, v124, v175, s[4:5]
	v_cndmask_b32_e64 v115, v121, v125, s[4:5]
	v_mov_b32_e32 v175, v155
	s_nop 1
	v_mov_b32_dpp v175, v115 row_ror:8 row_mask:0xf bank_mask:0xf
	v_cndmask_b32_e64 v121, v175, v121, s[4:5]
	v_cndmask_b32_e64 v125, v125, v175, s[4:5]
	v_cndmask_b32_e64 v115, v122, v126, s[4:5]
	v_mov_b32_e32 v175, v155
	s_nop 1
	v_mov_b32_dpp v175, v115 row_ror:8 row_mask:0xf bank_mask:0xf
	v_cndmask_b32_e64 v122, v175, v122, s[4:5]
	v_cndmask_b32_e64 v126, v126, v175, s[4:5]
	v_cndmask_b32_e64 v115, v123, v127, s[4:5]
	v_mov_b32_e32 v175, v155
	s_nop 1
	v_mov_b32_dpp v175, v115 row_ror:8 row_mask:0xf bank_mask:0xf
	v_cndmask_b32_e64 v123, v175, v123, s[4:5]
	v_cndmask_b32_e64 v127, v127, v175, s[4:5]
	s_cmp_lg_u64 s[6:7], 0
	s_cbranch_scc0 .Lp1wt_8
	global_store_dwordx4 v[182:183], v[120:123], off
	s_branch .Lp1wt_8_e

.Lp1wt_9_e:
	v_add_u32_e32 v120, 0x90, v114
	v_ashrrev_i32_e32 v121, 31, v120
	v_lshlrev_b64 v[128:129], s0, v[120:121]
	v_cvt_pk_bf16_f32 v115, v46, v47
	v_cvt_pk_bf16_f32 v121, v48, v49
	v_cvt_pk_bf16_f32 v122, v42, v43
	v_cvt_pk_bf16_f32 v123, v44, v45
	v_cvt_pk_bf16_f32 v124, v38, v39
	v_cvt_pk_bf16_f32 v125, v40, v41
	v_cvt_pk_bf16_f32 v126, v34, v35
	v_cvt_pk_bf16_f32 v127, v36, v37
	v_lshl_add_u64 v[128:129], v[128:129], 1, v[116:117]
	v_cndmask_b32_e64 v120, v115, v124, s[4:5]
	v_lshl_add_u64 v[182:183], v[128:129], 0, v[118:119]
	s_nop 0
	v_mov_b32_dpp v175, v120 row_ror:8 row_mask:0xf bank_mask:0xf
	v_cndmask_b32_e64 v120, v175, v115, s[4:5]
	v_cndmask_b32_e64 v124, v124, v175, s[4:5]
	v_cndmask_b32_e64 v115, v121, v125, s[4:5]
	v_mov_b32_e32 v175, v155
	s_nop 1
	v_mov_b32_dpp v175, v115 row_ror:8 row_mask:0xf bank_mask:0xf
	v_cndmask_b32_e64 v121, v175, v121, s[4:5]
	v_cndmask_b32_e64 v125, v125, v175, s[4:5]
	v_cndmask_b32_e64 v115, v122, v126, s[4:5]
	v_mov_b32_e32 v175, v155
	s_nop 1
	v_mov_b32_dpp v175, v115 row_ror:8 row_mask:0xf bank_mask:0xf
	v_cndmask_b32_e64 v122, v175, v122, s[4:5]
	v_cndmask_b32_e64 v126, v126, v175, s[4:5]
	v_cndmask_b32_e64 v115, v123, v127, s[4:5]
	v_mov_b32_e32 v175, v155
	s_nop 1
	v_mov_b32_dpp v175, v115 row_ror:8 row_mask:0xf bank_mask:0xf
	v_cndmask_b32_e64 v123, v175, v123, s[4:5]
	v_cndmask_b32_e64 v127, v127, v175, s[4:5]
	s_cmp_lg_u64 s[6:7], 0
	s_cbranch_scc0 .Lp1wt_10
	global_store_dwordx4 v[182:183], v[120:123], off
	s_branch .Lp1wt_10_e

.Lp1wt_11_e:
	v_add_u32_e32 v120, 0xa0, v114
	v_ashrrev_i32_e32 v121, 31, v120
	v_lshlrev_b64 v[128:129], s0, v[120:121]
	v_cvt_pk_bf16_f32 v115, v30, v31
	v_cvt_pk_bf16_f32 v121, v32, v33
	v_cvt_pk_bf16_f32 v122, v26, v27
	v_cvt_pk_bf16_f32 v123, v28, v29
	v_cvt_pk_bf16_f32 v124, v22, v23
	v_cvt_pk_bf16_f32 v125, v24, v25
	v_cvt_pk_bf16_f32 v126, v18, v19
	v_cvt_pk_bf16_f32 v127, v20, v21
	v_lshl_add_u64 v[128:129], v[128:129], 1, v[116:117]
	v_cndmask_b32_e64 v120, v115, v124, s[4:5]
	v_lshl_add_u64 v[182:183], v[128:129], 0, v[118:119]
	s_nop 0
	v_mov_b32_dpp v175, v120 row_ror:8 row_mask:0xf bank_mask:0xf
	v_cndmask_b32_e64 v120, v175, v115, s[4:5]
	v_cndmask_b32_e64 v124, v124, v175, s[4:5]
	v_cndmask_b32_e64 v115, v121, v125, s[4:5]
	v_mov_b32_e32 v175, v155
	s_nop 1
	v_mov_b32_dpp v175, v115 row_ror:8 row_mask:0xf bank_mask:0xf
	v_cndmask_b32_e64 v121, v175, v121, s[4:5]
	v_cndmask_b32_e64 v125, v125, v175, s[4:5]
	v_cndmask_b32_e64 v115, v122, v126, s[4:5]
	v_mov_b32_e32 v175, v155
	s_nop 1
	v_mov_b32_dpp v175, v115 row_ror:8 row_mask:0xf bank_mask:0xf
	v_cndmask_b32_e64 v122, v175, v122, s[4:5]
	v_cndmask_b32_e64 v126, v126, v175, s[4:5]
	v_cndmask_b32_e64 v115, v123, v127, s[4:5]
	v_mov_b32_e32 v175, v155
	s_nop 1
	v_mov_b32_dpp v175, v115 row_ror:8 row_mask:0xf bank_mask:0xf
	v_cndmask_b32_e64 v123, v175, v123, s[4:5]
	v_cndmask_b32_e64 v127, v127, v175, s[4:5]
	s_cmp_lg_u64 s[6:7], 0
	s_cbranch_scc0 .Lp1wt_12
	global_store_dwordx4 v[182:183], v[120:123], off
	s_branch .Lp1wt_12_e

.Lp1wt_13_e:
	v_add_u32_e32 v120, 0xb0, v114
	v_ashrrev_i32_e32 v121, 31, v120
	v_lshlrev_b64 v[128:129], s0, v[120:121]
	v_cvt_pk_bf16_f32 v115, v14, v15
	v_cvt_pk_bf16_f32 v121, v16, v17
	v_cvt_pk_bf16_f32 v122, v10, v11
	v_cvt_pk_bf16_f32 v123, v12, v13
	v_cvt_pk_bf16_f32 v124, v6, v7
	v_cvt_pk_bf16_f32 v125, v8, v9
	v_cvt_pk_bf16_f32 v126, v2, v3
	v_cvt_pk_bf16_f32 v127, v4, v5
	v_lshl_add_u64 v[116:117], v[128:129], 1, v[116:117]
	v_cndmask_b32_e64 v120, v115, v124, s[4:5]
	v_lshl_add_u64 v[118:119], v[116:117], 0, v[118:119]
	v_lshl_add_u64 v[116:117], v[116:117], 0, v[154:155]
	v_mov_b32_dpp v175, v120 row_ror:8 row_mask:0xf bank_mask:0xf
	v_cndmask_b32_e64 v120, v175, v115, s[4:5]
	v_cndmask_b32_e64 v124, v124, v175, s[4:5]
	v_cndmask_b32_e64 v115, v121, v125, s[4:5]
	v_mov_b32_e32 v175, v155
	s_nop 1
	v_mov_b32_dpp v175, v115 row_ror:8 row_mask:0xf bank_mask:0xf
	v_cndmask_b32_e64 v121, v175, v121, s[4:5]
	v_cndmask_b32_e64 v125, v125, v175, s[4:5]
	v_cndmask_b32_e64 v115, v122, v126, s[4:5]
	v_mov_b32_e32 v175, v155
	s_nop 1
	v_mov_b32_dpp v175, v115 row_ror:8 row_mask:0xf bank_mask:0xf
	v_cndmask_b32_e64 v122, v175, v122, s[4:5]
	v_cndmask_b32_e64 v126, v126, v175, s[4:5]
	v_cndmask_b32_e64 v115, v123, v127, s[4:5]
	v_mov_b32_e32 v175, v155
	s_nop 1
	v_mov_b32_dpp v175, v115 row_ror:8 row_mask:0xf bank_mask:0xf
	v_cndmask_b32_e64 v123, v175, v123, s[4:5]
	v_cndmask_b32_e64 v127, v127, v175, s[4:5]
	s_cmp_lg_u64 s[6:7], 0
	s_cbranch_scc0 .Lp1wt_14
	global_store_dwordx4 v[118:119], v[120:123], off
	s_branch .Lp1wt_14_e
.Lp1wt_14:
	global_store_dwordx4 v[118:119], v[120:123], off sc0 sc1
.Lp1wt_14_e:
	s_cmp_lg_u64 s[6:7], 0
	s_cbranch_scc0 .Lp1wt_15
	global_store_dwordx4 v[116:117], v[124:127], off
	s_branch .Lp1wt_15_e
.Lp1wt_15:
	global_store_dwordx4 v[116:117], v[124:127], off sc0 sc1
.Lp1wt_15_e:
	s_cbranch_execz .LBB0_172
.LBB0_170:
	s_andn2_b64 vcc, exec, s[6:7]
	s_mov_b64 s[0:1], -1
	s_cbranch_vccnz .LBB0_161
	s_branch .LBB0_205

.Lrope_pf2:
	s_lshl_b32 s1, s68, 1
	s_and_b32 s1, s1, 6
	s_or_b32 s1, s50, s1
	s_lshl_b32 s0, s0, 5
	s_or_b32 s0, s1, s0
	s_lshr_b32 s1, s12, 9
	s_and_b32 s1, s1, 0xffff8
	s_add_i32 s1, s1, s0
	s_lshl_b32 s1, s1, 12
	s_cmp_lt_u32 s68, 4
	s_cselect_b64 vcc, -1, 0
	v_cndmask_b32_e32 v175, 1.0, v181, vcc
	v_mul_f32_e32 v142, v175, v142
	v_mul_f32_e32 v143, v175, v143
	v_cvt_pk_bf16_f32 v142, v142, v143
	v_mul_f32_e32 v143, v175, v144
	v_mul_f32_e32 v144, v175, v145
	v_mul_f32_e32 v138, v175, v138
	v_mul_f32_e32 v139, v175, v139
	v_mul_f32_e32 v134, v175, v134
	v_mul_f32_e32 v135, v175, v135
	v_cvt_pk_bf16_f32 v143, v143, v144
	v_cvt_pk_bf16_f32 v144, v138, v139
	v_mul_f32_e32 v138, v175, v140
	v_mul_f32_e32 v139, v175, v141
	v_cvt_pk_bf16_f32 v140, v138, v139
	v_cvt_pk_bf16_f32 v134, v134, v135
	v_mul_f32_e32 v135, v175, v136
	v_mul_f32_e32 v136, v175, v137
	v_mul_f32_e32 v130, v175, v130
	v_mul_f32_e32 v131, v175, v131
	v_cvt_pk_bf16_f32 v135, v135, v136
	v_cvt_pk_bf16_f32 v136, v130, v131
	v_mul_f32_e32 v130, v175, v132
	v_mul_f32_e32 v131, v175, v133
	v_cvt_pk_bf16_f32 v137, v130, v131
	v_cndmask_b32_e64 v130, v142, v134, s[4:5]
	v_mov_b32_e32 v131, 0
	v_mov_b32_e32 v132, 0
	v_or_b32_e32 v184, s1, v182
	v_mov_b32_dpp v131, v130 row_ror:8 row_mask:0xf bank_mask:0xf
	v_cndmask_b32_e64 v130, v131, v142, s[4:5]
	v_cndmask_b32_e64 v134, v134, v131, s[4:5]
	v_cndmask_b32_e64 v131, v143, v135, s[4:5]
	v_mov_b32_e32 v133, 0
	v_ashrrev_i32_e32 v185, 31, v184
	v_mov_b32_dpp v132, v131 row_ror:8 row_mask:0xf bank_mask:0xf
	v_cndmask_b32_e64 v131, v132, v143, s[4:5]
	v_cndmask_b32_e64 v135, v135, v132, s[4:5]
	v_cndmask_b32_e64 v132, v144, v136, s[4:5]
	v_lshlrev_b64 v[184:185], 8, v[184:185]
	v_mov_b32_e32 v141, 0
	v_mov_b32_dpp v133, v132 row_ror:8 row_mask:0xf bank_mask:0xf
	v_cndmask_b32_e64 v132, v133, v144, s[4:5]
	v_cndmask_b32_e64 v136, v136, v133, s[4:5]
	v_cndmask_b32_e64 v133, v140, v137, s[4:5]
	v_lshl_add_u64 v[138:139], v[162:163], 0, v[184:185]
	v_lshlrev_b32_e32 v154, 1, v158
	v_mov_b32_dpp v141, v133 row_ror:8 row_mask:0xf bank_mask:0xf
	v_cndmask_b32_e64 v133, v141, v140, s[4:5]
	v_cndmask_b32_e64 v137, v137, v141, s[4:5]
	v_lshl_add_u64 v[140:141], v[156:157], 1, v[138:139]
	s_cmp_lg_u64 s[6:7], 0
	s_cbranch_scc0 .Lp1wt_16
	global_store_dwordx4 v[140:141], v[130:133], off
	s_branch .Lp1wt_16_e
.Lp1wt_16:
	global_store_dwordx4 v[140:141], v[130:133], off sc0 sc1
.Lp1wt_16_e:
	s_and_b64 vcc, exec, s[8:9]
	s_nop 0
	v_lshl_add_u64 v[130:131], v[138:139], 0, v[154:155]
	s_cmp_lg_u64 s[6:7], 0
	s_cbranch_scc0 .Lp1wt_17
	global_store_dwordx4 v[130:131], v[134:137], off
	s_branch .Lp1wt_17_e
.Lp1wt_17:
	global_store_dwordx4 v[130:131], v[134:137], off sc0 sc1
.Lp1wt_17_e:
	v_or_b32_e32 v130, 16, v182
	s_cbranch_vccnz .LBB0_178

.Lrope_pf3:
	v_mul_f32_e32 v110, v175, v110
	v_mul_f32_e32 v111, v175, v111
	v_cvt_pk_bf16_f32 v110, v110, v111
	v_mul_f32_e32 v111, v175, v112
	v_mul_f32_e32 v112, v175, v113
	v_mul_f32_e32 v106, v175, v106
	v_mul_f32_e32 v107, v175, v107
	v_mul_f32_e32 v102, v175, v102
	v_mul_f32_e32 v103, v175, v103
	v_cvt_pk_bf16_f32 v111, v111, v112
	v_cvt_pk_bf16_f32 v112, v106, v107
	v_mul_f32_e32 v106, v175, v108
	v_mul_f32_e32 v107, v175, v109
	v_cvt_pk_bf16_f32 v108, v106, v107
	v_cvt_pk_bf16_f32 v102, v102, v103
	v_mul_f32_e32 v103, v175, v104
	v_mul_f32_e32 v104, v175, v105
	v_mul_f32_e32 v98, v175, v98
	v_mul_f32_e32 v99, v175, v99
	v_cvt_pk_bf16_f32 v103, v103, v104
	v_cvt_pk_bf16_f32 v104, v98, v99
	v_mul_f32_e32 v98, v175, v100
	v_mul_f32_e32 v99, v175, v101
	v_cvt_pk_bf16_f32 v105, v98, v99
	v_cndmask_b32_e64 v98, v110, v102, s[4:5]
	v_mov_b32_e32 v99, v155
	v_mov_b32_e32 v100, v155
	v_or_b32_e32 v130, s1, v130
	v_mov_b32_dpp v99, v98 row_ror:8 row_mask:0xf bank_mask:0xf
	v_cndmask_b32_e64 v98, v99, v110, s[4:5]
	v_cndmask_b32_e64 v102, v102, v99, s[4:5]
	v_cndmask_b32_e64 v99, v111, v103, s[4:5]
	v_mov_b32_e32 v101, v155
	v_ashrrev_i32_e32 v131, 31, v130
	v_mov_b32_dpp v100, v99 row_ror:8 row_mask:0xf bank_mask:0xf
	v_cndmask_b32_e64 v99, v100, v111, s[4:5]
	v_cndmask_b32_e64 v103, v103, v100, s[4:5]
	v_cndmask_b32_e64 v100, v112, v104, s[4:5]
	v_lshlrev_b64 v[130:131], 8, v[130:131]
	v_mov_b32_e32 v109, v155
	v_mov_b32_dpp v101, v100 row_ror:8 row_mask:0xf bank_mask:0xf
	v_cndmask_b32_e64 v100, v101, v112, s[4:5]
	v_cndmask_b32_e64 v104, v104, v101, s[4:5]
	v_cndmask_b32_e64 v101, v108, v105, s[4:5]
	v_lshl_add_u64 v[106:107], v[162:163], 0, v[130:131]
	s_and_b64 vcc, exec, s[8:9]
	v_mov_b32_dpp v109, v101 row_ror:8 row_mask:0xf bank_mask:0xf
	v_cndmask_b32_e64 v101, v109, v108, s[4:5]
	v_cndmask_b32_e64 v105, v105, v109, s[4:5]
	v_lshl_add_u64 v[108:109], v[156:157], 1, v[106:107]
	s_cmp_lg_u64 s[6:7], 0
	s_cbranch_scc0 .Lp1wt_18
	global_store_dwordx4 v[108:109], v[98:101], off
	s_branch .Lp1wt_18_e
.Lp1wt_18:
	global_store_dwordx4 v[108:109], v[98:101], off sc0 sc1
.Lp1wt_18_e:
	s_nop 1
	v_lshl_add_u64 v[98:99], v[106:107], 0, v[154:155]
	s_cmp_lg_u64 s[6:7], 0
	s_cbranch_scc0 .Lp1wt_19
	global_store_dwordx4 v[98:99], v[102:105], off
	s_branch .Lp1wt_19_e
.Lp1wt_19:
	global_store_dwordx4 v[98:99], v[102:105], off sc0 sc1
.Lp1wt_19_e:
	v_or_b32_e32 v98, 32, v182
	s_cbranch_vccnz .LBB0_182

.Lrope_pf4:
	v_mul_f32_e32 v94, v175, v94
	v_mul_f32_e32 v95, v175, v95
	v_cvt_pk_bf16_f32 v94, v94, v95
	v_mul_f32_e32 v95, v175, v96
	v_mul_f32_e32 v96, v175, v97
	v_mul_f32_e32 v90, v175, v90
	v_mul_f32_e32 v91, v175, v91
	v_mul_f32_e32 v86, v175, v86
	v_mul_f32_e32 v87, v175, v87
	v_cvt_pk_bf16_f32 v95, v95, v96
	v_cvt_pk_bf16_f32 v96, v90, v91
	v_mul_f32_e32 v90, v175, v92
	v_mul_f32_e32 v91, v175, v93
	v_cvt_pk_bf16_f32 v92, v90, v91
	v_cvt_pk_bf16_f32 v86, v86, v87
	v_mul_f32_e32 v87, v175, v88
	v_mul_f32_e32 v88, v175, v89
	v_mul_f32_e32 v82, v175, v82
	v_mul_f32_e32 v83, v175, v83
	v_cvt_pk_bf16_f32 v87, v87, v88
	v_cvt_pk_bf16_f32 v88, v82, v83
	v_mul_f32_e32 v82, v175, v84
	v_mul_f32_e32 v83, v175, v85
	v_cvt_pk_bf16_f32 v89, v82, v83
	v_cndmask_b32_e64 v82, v94, v86, s[4:5]
	v_mov_b32_e32 v83, v155
	v_mov_b32_e32 v84, v155
	v_or_b32_e32 v98, s1, v98
	v_mov_b32_dpp v83, v82 row_ror:8 row_mask:0xf bank_mask:0xf
	v_cndmask_b32_e64 v82, v83, v94, s[4:5]
	v_cndmask_b32_e64 v86, v86, v83, s[4:5]
	v_cndmask_b32_e64 v83, v95, v87, s[4:5]
	v_mov_b32_e32 v85, v155
	v_ashrrev_i32_e32 v99, 31, v98
	v_mov_b32_dpp v84, v83 row_ror:8 row_mask:0xf bank_mask:0xf
	v_cndmask_b32_e64 v83, v84, v95, s[4:5]
	v_cndmask_b32_e64 v87, v87, v84, s[4:5]
	v_cndmask_b32_e64 v84, v96, v88, s[4:5]
	v_lshlrev_b64 v[98:99], 8, v[98:99]
	v_mov_b32_e32 v93, v155
	v_mov_b32_dpp v85, v84 row_ror:8 row_mask:0xf bank_mask:0xf
	v_cndmask_b32_e64 v84, v85, v96, s[4:5]
	v_cndmask_b32_e64 v88, v88, v85, s[4:5]
	v_cndmask_b32_e64 v85, v92, v89, s[4:5]
	v_lshl_add_u64 v[90:91], v[162:163], 0, v[98:99]
	s_and_b64 vcc, exec, s[8:9]
	v_mov_b32_dpp v93, v85 row_ror:8 row_mask:0xf bank_mask:0xf
	v_cndmask_b32_e64 v85, v93, v92, s[4:5]
	v_cndmask_b32_e64 v89, v89, v93, s[4:5]
	v_lshl_add_u64 v[92:93], v[156:157], 1, v[90:91]
	s_cmp_lg_u64 s[6:7], 0
	s_cbranch_scc0 .Lp1wt_20
	global_store_dwordx4 v[92:93], v[82:85], off
	s_branch .Lp1wt_20_e
.Lp1wt_20:
	global_store_dwordx4 v[92:93], v[82:85], off sc0 sc1
.Lp1wt_20_e:
	s_nop 1
	v_lshl_add_u64 v[82:83], v[90:91], 0, v[154:155]
	s_cmp_lg_u64 s[6:7], 0
	s_cbranch_scc0 .Lp1wt_21
	global_store_dwordx4 v[82:83], v[86:89], off
	s_branch .Lp1wt_21_e
.Lp1wt_21:
	global_store_dwordx4 v[82:83], v[86:89], off sc0 sc1
.Lp1wt_21_e:
	v_or_b32_e32 v82, 48, v182
	s_cbranch_vccnz .LBB0_186

.Lrope_pf5:
	v_mul_f32_e32 v78, v175, v78
	v_mul_f32_e32 v79, v175, v79
	v_cvt_pk_bf16_f32 v78, v78, v79
	v_mul_f32_e32 v79, v175, v80
	v_mul_f32_e32 v80, v175, v81
	v_mul_f32_e32 v74, v175, v74
	v_mul_f32_e32 v75, v175, v75
	v_mul_f32_e32 v70, v175, v70
	v_mul_f32_e32 v71, v175, v71
	v_cvt_pk_bf16_f32 v79, v79, v80
	v_cvt_pk_bf16_f32 v80, v74, v75
	v_mul_f32_e32 v74, v175, v76
	v_mul_f32_e32 v75, v175, v77
	v_cvt_pk_bf16_f32 v76, v74, v75
	v_cvt_pk_bf16_f32 v70, v70, v71
	v_mul_f32_e32 v71, v175, v72
	v_mul_f32_e32 v72, v175, v73
	v_mul_f32_e32 v66, v175, v66
	v_mul_f32_e32 v67, v175, v67
	v_cvt_pk_bf16_f32 v71, v71, v72
	v_cvt_pk_bf16_f32 v72, v66, v67
	v_mul_f32_e32 v66, v175, v68
	v_mul_f32_e32 v67, v175, v69
	v_cvt_pk_bf16_f32 v73, v66, v67
	v_cndmask_b32_e64 v66, v78, v70, s[4:5]
	v_mov_b32_e32 v67, v155
	v_mov_b32_e32 v68, v155
	v_or_b32_e32 v82, s1, v82
	v_mov_b32_dpp v67, v66 row_ror:8 row_mask:0xf bank_mask:0xf
	v_cndmask_b32_e64 v66, v67, v78, s[4:5]
	v_cndmask_b32_e64 v70, v70, v67, s[4:5]
	v_cndmask_b32_e64 v67, v79, v71, s[4:5]
	v_mov_b32_e32 v69, v155
	v_ashrrev_i32_e32 v83, 31, v82
	v_mov_b32_dpp v68, v67 row_ror:8 row_mask:0xf bank_mask:0xf
	v_cndmask_b32_e64 v67, v68, v79, s[4:5]
	v_cndmask_b32_e64 v71, v71, v68, s[4:5]
	v_cndmask_b32_e64 v68, v80, v72, s[4:5]
	v_lshlrev_b64 v[82:83], 8, v[82:83]
	v_mov_b32_e32 v77, v155
	v_mov_b32_dpp v69, v68 row_ror:8 row_mask:0xf bank_mask:0xf
	v_cndmask_b32_e64 v68, v69, v80, s[4:5]
	v_cndmask_b32_e64 v72, v72, v69, s[4:5]
	v_cndmask_b32_e64 v69, v76, v73, s[4:5]
	v_lshl_add_u64 v[74:75], v[162:163], 0, v[82:83]
	s_and_b64 vcc, exec, s[8:9]
	v_mov_b32_dpp v77, v69 row_ror:8 row_mask:0xf bank_mask:0xf
	v_cndmask_b32_e64 v69, v77, v76, s[4:5]
	v_cndmask_b32_e64 v73, v73, v77, s[4:5]
	v_lshl_add_u64 v[76:77], v[156:157], 1, v[74:75]
	s_cmp_lg_u64 s[6:7], 0
	s_cbranch_scc0 .Lp1wt_22
	global_store_dwordx4 v[76:77], v[66:69], off
	s_branch .Lp1wt_22_e
.Lp1wt_22:
	global_store_dwordx4 v[76:77], v[66:69], off sc0 sc1
.Lp1wt_22_e:
	s_nop 1
	v_lshl_add_u64 v[66:67], v[74:75], 0, v[154:155]
	s_cmp_lg_u64 s[6:7], 0
	s_cbranch_scc0 .Lp1wt_23
	global_store_dwordx4 v[66:67], v[70:73], off
	s_branch .Lp1wt_23_e
.Lp1wt_23:
	global_store_dwordx4 v[66:67], v[70:73], off sc0 sc1
.Lp1wt_23_e:
	v_and_b32_e32 v66, 0xfcf, v174
	s_cbranch_vccnz .LBB0_190

.Lrope_pf6:
	v_mul_f32_e32 v62, v175, v62
	v_mul_f32_e32 v63, v175, v63
	v_cvt_pk_bf16_f32 v62, v62, v63
	v_mul_f32_e32 v63, v175, v64
	v_mul_f32_e32 v64, v175, v65
	v_mul_f32_e32 v58, v175, v58
	v_mul_f32_e32 v59, v175, v59
	v_mul_f32_e32 v54, v175, v54
	v_mul_f32_e32 v55, v175, v55
	v_cvt_pk_bf16_f32 v63, v63, v64
	v_cvt_pk_bf16_f32 v64, v58, v59
	v_mul_f32_e32 v58, v175, v60
	v_mul_f32_e32 v59, v175, v61
	v_cvt_pk_bf16_f32 v60, v58, v59
	v_cvt_pk_bf16_f32 v54, v54, v55
	v_mul_f32_e32 v55, v175, v56
	v_mul_f32_e32 v56, v175, v57
	v_mul_f32_e32 v50, v175, v50
	v_mul_f32_e32 v51, v175, v51
	v_cvt_pk_bf16_f32 v55, v55, v56
	v_cvt_pk_bf16_f32 v56, v50, v51
	v_mul_f32_e32 v50, v175, v52
	v_mul_f32_e32 v51, v175, v53
	v_cvt_pk_bf16_f32 v57, v50, v51
	v_cndmask_b32_e64 v50, v62, v54, s[4:5]
	v_mov_b32_e32 v51, v155
	v_lshrrev_b32_e32 v67, 9, v174
	v_and_b32_e32 v67, 0xffff8, v67
	v_mov_b32_dpp v51, v50 row_ror:8 row_mask:0xf bank_mask:0xf
	v_cndmask_b32_e64 v50, v51, v62, s[4:5]
	v_cndmask_b32_e64 v54, v54, v51, s[4:5]
	v_cndmask_b32_e64 v51, v63, v55, s[4:5]
	v_mov_b32_e32 v52, v155
	v_add_lshl_u32 v67, v67, s0, 12
	v_or_b32_e32 v68, v67, v66
	v_mov_b32_dpp v52, v51 row_ror:8 row_mask:0xf bank_mask:0xf
	v_cndmask_b32_e64 v51, v52, v63, s[4:5]
	v_cndmask_b32_e64 v55, v55, v52, s[4:5]
	v_cndmask_b32_e64 v52, v64, v56, s[4:5]
	v_mov_b32_e32 v53, v155
	v_ashrrev_i32_e32 v69, 31, v68
	v_lshlrev_b64 v[68:69], 8, v[68:69]
	v_mov_b32_dpp v53, v52 row_ror:8 row_mask:0xf bank_mask:0xf
	v_cndmask_b32_e64 v52, v53, v64, s[4:5]
	v_cndmask_b32_e64 v56, v56, v53, s[4:5]
	v_cndmask_b32_e64 v53, v60, v57, s[4:5]
	v_mov_b32_e32 v61, v155
	v_lshl_add_u64 v[58:59], v[162:163], 0, v[68:69]
	s_and_b64 vcc, exec, s[8:9]
	v_mov_b32_dpp v61, v53 row_ror:8 row_mask:0xf bank_mask:0xf
	v_cndmask_b32_e64 v53, v61, v60, s[4:5]
	v_cndmask_b32_e64 v57, v57, v61, s[4:5]
	v_lshl_add_u64 v[60:61], v[156:157], 1, v[58:59]
	s_cmp_lg_u64 s[6:7], 0
	s_cbranch_scc0 .Lp1wt_24
	global_store_dwordx4 v[60:61], v[50:53], off
	s_branch .Lp1wt_24_e
.Lp1wt_24:
	global_store_dwordx4 v[60:61], v[50:53], off sc0 sc1
.Lp1wt_24_e:
	s_nop 1
	v_lshl_add_u64 v[50:51], v[58:59], 0, v[154:155]
	s_cmp_lg_u64 s[6:7], 0
	s_cbranch_scc0 .Lp1wt_25
	global_store_dwordx4 v[50:51], v[54:57], off
	s_branch .Lp1wt_25_e
.Lp1wt_25:
	global_store_dwordx4 v[50:51], v[54:57], off sc0 sc1
.Lp1wt_25_e:
	v_or_b32_e32 v50, 16, v66
	s_cbranch_vccnz .LBB0_194

.Lrope_pf7:
	v_mul_f32_e32 v46, v175, v46
	v_mul_f32_e32 v47, v175, v47
	v_cvt_pk_bf16_f32 v46, v46, v47
	v_mul_f32_e32 v47, v175, v48
	v_mul_f32_e32 v48, v175, v49
	v_mul_f32_e32 v42, v175, v42
	v_mul_f32_e32 v43, v175, v43
	v_mul_f32_e32 v38, v175, v38
	v_mul_f32_e32 v39, v175, v39
	v_cvt_pk_bf16_f32 v47, v47, v48
	v_cvt_pk_bf16_f32 v48, v42, v43
	v_mul_f32_e32 v42, v175, v44
	v_mul_f32_e32 v43, v175, v45
	v_cvt_pk_bf16_f32 v44, v42, v43
	v_cvt_pk_bf16_f32 v38, v38, v39
	v_mul_f32_e32 v39, v175, v40
	v_mul_f32_e32 v40, v175, v41
	v_mul_f32_e32 v34, v175, v34
	v_mul_f32_e32 v35, v175, v35
	v_cvt_pk_bf16_f32 v39, v39, v40
	v_cvt_pk_bf16_f32 v40, v34, v35
	v_mul_f32_e32 v34, v175, v36
	v_mul_f32_e32 v35, v175, v37
	v_cvt_pk_bf16_f32 v41, v34, v35
	v_cndmask_b32_e64 v34, v46, v38, s[4:5]
	v_mov_b32_e32 v35, v155
	v_mov_b32_e32 v36, v155
	v_or_b32_e32 v50, v67, v50
	v_mov_b32_dpp v35, v34 row_ror:8 row_mask:0xf bank_mask:0xf
	v_cndmask_b32_e64 v34, v35, v46, s[4:5]
	v_cndmask_b32_e64 v38, v38, v35, s[4:5]
	v_cndmask_b32_e64 v35, v47, v39, s[4:5]
	v_mov_b32_e32 v37, v155
	v_ashrrev_i32_e32 v51, 31, v50
	v_mov_b32_dpp v36, v35 row_ror:8 row_mask:0xf bank_mask:0xf
	v_cndmask_b32_e64 v35, v36, v47, s[4:5]
	v_cndmask_b32_e64 v39, v39, v36, s[4:5]
	v_cndmask_b32_e64 v36, v48, v40, s[4:5]
	v_lshlrev_b64 v[50:51], 8, v[50:51]
	v_mov_b32_e32 v45, v155
	v_mov_b32_dpp v37, v36 row_ror:8 row_mask:0xf bank_mask:0xf
	v_cndmask_b32_e64 v36, v37, v48, s[4:5]
	v_cndmask_b32_e64 v40, v40, v37, s[4:5]
	v_cndmask_b32_e64 v37, v44, v41, s[4:5]
	v_lshl_add_u64 v[42:43], v[162:163], 0, v[50:51]
	s_and_b64 vcc, exec, s[8:9]
	v_mov_b32_dpp v45, v37 row_ror:8 row_mask:0xf bank_mask:0xf
	v_cndmask_b32_e64 v37, v45, v44, s[4:5]
	v_cndmask_b32_e64 v41, v41, v45, s[4:5]
	v_lshl_add_u64 v[44:45], v[156:157], 1, v[42:43]
	s_cmp_lg_u64 s[6:7], 0
	s_cbranch_scc0 .Lp1wt_26
	global_store_dwordx4 v[44:45], v[34:37], off
	s_branch .Lp1wt_26_e
.Lp1wt_26:
	global_store_dwordx4 v[44:45], v[34:37], off sc0 sc1
.Lp1wt_26_e:
	s_nop 1
	v_lshl_add_u64 v[34:35], v[42:43], 0, v[154:155]
	s_cmp_lg_u64 s[6:7], 0
	s_cbranch_scc0 .Lp1wt_27
	global_store_dwordx4 v[34:35], v[38:41], off
	s_branch .Lp1wt_27_e
.Lp1wt_27:
	global_store_dwordx4 v[34:35], v[38:41], off sc0 sc1
.Lp1wt_27_e:
	v_or_b32_e32 v34, 32, v66
	s_cbranch_vccnz .LBB0_198

.Lrope_pf8:
	v_mul_f32_e32 v30, v175, v30
	v_mul_f32_e32 v31, v175, v31
	v_cvt_pk_bf16_f32 v30, v30, v31
	v_mul_f32_e32 v31, v175, v32
	v_mul_f32_e32 v32, v175, v33
	v_mul_f32_e32 v26, v175, v26
	v_mul_f32_e32 v27, v175, v27
	v_mul_f32_e32 v22, v175, v22
	v_mul_f32_e32 v23, v175, v23
	v_cvt_pk_bf16_f32 v31, v31, v32
	v_cvt_pk_bf16_f32 v32, v26, v27
	v_mul_f32_e32 v26, v175, v28
	v_mul_f32_e32 v27, v175, v29
	v_cvt_pk_bf16_f32 v28, v26, v27
	v_cvt_pk_bf16_f32 v22, v22, v23
	v_mul_f32_e32 v23, v175, v24
	v_mul_f32_e32 v24, v175, v25
	v_mul_f32_e32 v18, v175, v18
	v_mul_f32_e32 v19, v175, v19
	v_cvt_pk_bf16_f32 v23, v23, v24
	v_cvt_pk_bf16_f32 v24, v18, v19
	v_mul_f32_e32 v18, v175, v20
	v_mul_f32_e32 v19, v175, v21
	v_cvt_pk_bf16_f32 v25, v18, v19
	v_cndmask_b32_e64 v18, v30, v22, s[4:5]
	v_mov_b32_e32 v19, v155
	v_mov_b32_e32 v20, v155
	v_or_b32_e32 v34, v67, v34
	v_mov_b32_dpp v19, v18 row_ror:8 row_mask:0xf bank_mask:0xf
	v_cndmask_b32_e64 v18, v19, v30, s[4:5]
	v_cndmask_b32_e64 v22, v22, v19, s[4:5]
	v_cndmask_b32_e64 v19, v31, v23, s[4:5]
	v_mov_b32_e32 v21, v155
	v_ashrrev_i32_e32 v35, 31, v34
	v_mov_b32_dpp v20, v19 row_ror:8 row_mask:0xf bank_mask:0xf
	v_cndmask_b32_e64 v19, v20, v31, s[4:5]
	v_cndmask_b32_e64 v23, v23, v20, s[4:5]
	v_cndmask_b32_e64 v20, v32, v24, s[4:5]
	v_lshlrev_b64 v[34:35], 8, v[34:35]
	v_mov_b32_e32 v29, v155
	v_mov_b32_dpp v21, v20 row_ror:8 row_mask:0xf bank_mask:0xf
	v_cndmask_b32_e64 v20, v21, v32, s[4:5]
	v_cndmask_b32_e64 v24, v24, v21, s[4:5]
	v_cndmask_b32_e64 v21, v28, v25, s[4:5]
	v_lshl_add_u64 v[26:27], v[162:163], 0, v[34:35]
	s_and_b64 vcc, exec, s[8:9]
	v_mov_b32_dpp v29, v21 row_ror:8 row_mask:0xf bank_mask:0xf
	v_cndmask_b32_e64 v21, v29, v28, s[4:5]
	v_cndmask_b32_e64 v25, v25, v29, s[4:5]
	v_lshl_add_u64 v[28:29], v[156:157], 1, v[26:27]
	s_cmp_lg_u64 s[6:7], 0
	s_cbranch_scc0 .Lp1wt_28
	global_store_dwordx4 v[28:29], v[18:21], off
	s_branch .Lp1wt_28_e
.Lp1wt_28:
	global_store_dwordx4 v[28:29], v[18:21], off sc0 sc1
.Lp1wt_28_e:
	s_nop 1
	v_lshl_add_u64 v[18:19], v[26:27], 0, v[154:155]
	s_cmp_lg_u64 s[6:7], 0
	s_cbranch_scc0 .Lp1wt_29
	global_store_dwordx4 v[18:19], v[22:25], off
	s_branch .Lp1wt_29_e
.Lp1wt_29:
	global_store_dwordx4 v[18:19], v[22:25], off sc0 sc1
.Lp1wt_29_e:
	v_or_b32_e32 v18, 48, v66
	s_cbranch_vccnz .LBB0_202

.LBB0_204:
	v_mul_f32_e32 v14, v175, v14
	v_mul_f32_e32 v15, v175, v15
	v_cvt_pk_bf16_f32 v14, v14, v15
	v_mul_f32_e32 v15, v175, v16
	v_mul_f32_e32 v16, v175, v17
	v_mul_f32_e32 v10, v175, v10
	v_mul_f32_e32 v11, v175, v11
	v_mul_f32_e32 v6, v175, v6
	v_mul_f32_e32 v7, v175, v7
	v_cvt_pk_bf16_f32 v15, v15, v16
	v_cvt_pk_bf16_f32 v16, v10, v11
	v_mul_f32_e32 v10, v175, v12
	v_mul_f32_e32 v11, v175, v13
	v_cvt_pk_bf16_f32 v12, v10, v11
	v_cvt_pk_bf16_f32 v6, v6, v7
	v_mul_f32_e32 v7, v175, v8
	v_mul_f32_e32 v8, v175, v9
	v_mul_f32_e32 v2, v175, v2
	v_mul_f32_e32 v3, v175, v3
	v_cvt_pk_bf16_f32 v7, v7, v8
	v_cvt_pk_bf16_f32 v8, v2, v3
	v_mul_f32_e32 v2, v175, v4
	v_mul_f32_e32 v3, v175, v5
	v_cvt_pk_bf16_f32 v9, v2, v3
	v_cndmask_b32_e64 v2, v14, v6, s[4:5]
	v_mov_b32_e32 v3, v155
	v_mov_b32_e32 v4, v155
	v_or_b32_e32 v18, v67, v18
	v_mov_b32_dpp v3, v2 row_ror:8 row_mask:0xf bank_mask:0xf
	v_cndmask_b32_e64 v2, v3, v14, s[4:5]
	v_cndmask_b32_e64 v6, v6, v3, s[4:5]
	v_cndmask_b32_e64 v3, v15, v7, s[4:5]
	v_mov_b32_e32 v5, v155
	v_ashrrev_i32_e32 v19, 31, v18
	v_mov_b32_dpp v4, v3 row_ror:8 row_mask:0xf bank_mask:0xf
	v_cndmask_b32_e64 v3, v4, v15, s[4:5]
	v_cndmask_b32_e64 v7, v7, v4, s[4:5]
	v_cndmask_b32_e64 v4, v16, v8, s[4:5]
	v_lshlrev_b64 v[18:19], 8, v[18:19]
	v_mov_b32_e32 v13, v155
	v_mov_b32_dpp v5, v4 row_ror:8 row_mask:0xf bank_mask:0xf
	v_cndmask_b32_e64 v4, v5, v16, s[4:5]
	v_cndmask_b32_e64 v8, v8, v5, s[4:5]
	v_cndmask_b32_e64 v5, v12, v9, s[4:5]
	v_lshl_add_u64 v[10:11], v[162:163], 0, v[18:19]
	s_nop 0
	v_mov_b32_dpp v13, v5 row_ror:8 row_mask:0xf bank_mask:0xf
	v_cndmask_b32_e64 v5, v13, v12, s[4:5]
	v_cndmask_b32_e64 v9, v9, v13, s[4:5]
	v_lshl_add_u64 v[12:13], v[156:157], 1, v[10:11]
	s_cmp_lg_u64 s[6:7], 0
	s_cbranch_scc0 .Lp1wt_30
	global_store_dwordx4 v[12:13], v[2:5], off
	s_branch .Lp1wt_30_e
.Lp1wt_30:
	global_store_dwordx4 v[12:13], v[2:5], off sc0 sc1
.Lp1wt_30_e:
	s_nop 1
	v_lshl_add_u64 v[2:3], v[10:11], 0, v[154:155]
	s_cmp_lg_u64 s[6:7], 0
	s_cbranch_scc0 .Lp1wt_31
	global_store_dwordx4 v[2:3], v[6:9], off
	s_branch .Lp1wt_31_e
.Lp1wt_31:
	global_store_dwordx4 v[2:3], v[6:9], off sc0 sc1
.Lp1wt_31_e:
	s_andn2_b64 vcc, exec, s[6:7]
	s_mov_b64 s[0:1], -1
	s_cbranch_vccnz .LBB0_161
.LBB0_205:
	s_andn2_b64 vcc, exec, s[14:15]
	s_cbranch_vccnz .LBB0_160
	s_barrier
	s_branch .LBB0_160
